# phase 8/9: grid barrier replaced by per-M-tile arrival counters (phase-8 outputs stored write-through, readers acquire), so phase 8's 4 second-round tiles overlap phase 9; phase-9 sample units moved t
# speedup vs baseline: 1.0028x; 1.0028x over previous
; __device__ __forceinline__ unsigned pk2(float lo, float hi) { f32x2 v = {lo, hi}; bf16x2_t b = __builtin_convertvector(v, bf16x2_t); return __builtin_bit_cast(unsigned, b); }
; __device__ __forceinline__ float bflo(unsigned w) { return __uint_as_float(w << 16); }
; __device__ __forceinline__ float bfhi(unsigned w) { return __uint_as_float(w & 0xffff0000u); }
;     __device__ __forceinline__ void operator()(const f32x4 (&acc)[2][2][4][2], const Unit& u, int wr, int wc, int fr, int fq) const {
;         const int col0 = u.pn * 256 + wc * 32 + 8 * fq;
; #pragma unroll
;         for (int ai = 0; ai < 2; ++ai)
; #pragma unroll
;             for (int m = 0; m < 4; ++m) {
;                 const int row = u.pm * 256 + ai * 128 + wr * 64 + m * 16 + fr;
;                 if (row < MR) {
; #pragma unroll
;                     for (int bj = 0; bj < 2; ++bj) {
;                         const u32x4 gv = *(const u32x4*)(GATE + (size_t)row * 2048 + 1024 + col0 + bj * 128);
;                         const u32x4 tv = *(const u32x4*)(T + (size_t)row * DM + col0 + bj * 128);
;                         f32x4 a = (f32x4){bflo(tv.x), bfhi(tv.x), bflo(tv.y), bfhi(tv.y)}, b = (f32x4){bflo(tv.z), bfhi(tv.z), bflo(tv.w), bfhi(tv.w)};
;                         const f32x4 x = acc[ai][bj][m][0], y = acc[ai][bj][m][1];
;                         a[0] += x[0] * bflo(gv.x); a[1] += x[1] * bfhi(gv.x); a[2] += x[2] * bflo(gv.y); a[3] += x[3] * bfhi(gv.y);
;                         b[0] += y[0] * bflo(gv.z); b[1] += y[1] * bfhi(gv.z); b[2] += y[2] * bflo(gv.w); b[3] += y[3] * bfhi(gv.w);
;                         u32x4 w; w.x = pk2(a[0], a[1]); w.y = pk2(a[2], a[3]); w.z = pk2(b[0], b[1]); w.w = pk2(b[2], b[3]);
;                         *(u32x4*)(MG + (size_t)row * DM + col0 + bj * 128) = w;
;                     }
;                 }
;                 asm volatile("" ::: "memory");
;             }
.LBB0_2028:
	v_lshl_or_b32 v144, s26, 8, v150
	v_lshl_add_u32 v146, s40, 8, v148
	v_ashrrev_i32_e32 v145, 31, v144
	v_cmp_gt_i32_e32 vcc, s61, v146
	v_lshlrev_b64 v[144:145], 1, v[144:145]
	s_and_saveexec_b64 s[26:27], vcc
	s_cbranch_execz .LBB0_2030
	v_ashrrev_i32_e32 v147, 31, v146
	v_lshlrev_b64 v[154:155], 12, v[146:147]
	v_lshlrev_b64 v[170:171], 11, v[146:147]
	v_lshl_add_u64 v[158:159], s[10:11], 0, v[154:155]
	v_lshl_add_u64 v[154:155], s[8:9], 0, v[170:171]
	v_lshl_add_u64 v[162:163], v[154:155], 0, v[144:145]
	global_load_dwordx4 v[154:157], v[162:163], off
	v_lshl_add_u64 v[166:167], v[158:159], 0, v[144:145]
	global_load_dwordx4 v[158:161], v[166:167], off offset:2048
	s_nop 0
	global_load_dwordx4 v[162:165], v[162:163], off offset:256
	s_nop 0
	global_load_dwordx4 v[166:169], v[166:167], off offset:2304
	v_lshl_add_u64 v[170:171], s[12:13], 0, v[170:171]
	v_lshl_add_u64 v[170:171], v[170:171], 0, v[144:145]
	s_waitcnt vmcnt(0)
	v_lshlrev_b32_e32 v174, 16, v158
	v_lshlrev_b32_e32 v172, 16, v154
	v_and_b32_e32 v173, 0xffff0000, v154
	v_and_b32_e32 v175, 0xffff0000, v158
	v_lshlrev_b32_e32 v154, 16, v155
	v_and_b32_e32 v155, 0xffff0000, v155
	v_lshlrev_b32_e32 v158, 16, v159
	v_and_b32_e32 v159, 0xffff0000, v159
	v_lshlrev_b32_e32 v176, 16, v156
	v_and_b32_e32 v177, 0xffff0000, v156
	v_lshlrev_b32_e32 v178, 16, v160
	v_and_b32_e32 v179, 0xffff0000, v160
	v_lshlrev_b32_e32 v156, 16, v157
	v_and_b32_e32 v157, 0xffff0000, v157
	v_lshlrev_b32_e32 v160, 16, v161
	v_and_b32_e32 v161, 0xffff0000, v161
	v_lshlrev_b32_e32 v182, 16, v162
	v_and_b32_e32 v183, 0xffff0000, v162
	v_lshlrev_b32_e32 v184, 16, v166
	v_and_b32_e32 v185, 0xffff0000, v166
	v_lshlrev_b32_e32 v162, 16, v163
	v_and_b32_e32 v163, 0xffff0000, v163
	v_lshlrev_b32_e32 v166, 16, v167
	v_and_b32_e32 v167, 0xffff0000, v167
	v_lshlrev_b32_e32 v186, 16, v164
	v_and_b32_e32 v187, 0xffff0000, v164
	v_lshlrev_b32_e32 v188, 16, v168
	v_and_b32_e32 v189, 0xffff0000, v168
	v_lshlrev_b32_e32 v164, 16, v165
	v_and_b32_e32 v165, 0xffff0000, v165
	v_lshlrev_b32_e32 v168, 16, v169
	v_and_b32_e32 v169, 0xffff0000, v169
	v_pk_fma_f32 v[124:125], v[124:125], v[174:175], v[172:173]
	v_pk_fma_f32 v[126:127], v[126:127], v[158:159], v[154:155]
	v_pk_fma_f32 v[120:121], v[120:121], v[178:179], v[176:177]
	v_pk_fma_f32 v[122:123], v[122:123], v[160:161], v[156:157]
	v_pk_fma_f32 v[116:117], v[116:117], v[184:185], v[182:183]
	v_pk_fma_f32 v[118:119], v[118:119], v[166:167], v[162:163]
	v_pk_fma_f32 v[154:155], v[112:113], v[188:189], v[186:187]
	v_pk_fma_f32 v[156:157], v[114:115], v[168:169], v[164:165]
	v_cvt_pk_bf16_f32 v112, v124, v125
	v_cvt_pk_bf16_f32 v113, v126, v127
	v_cvt_pk_bf16_f32 v114, v120, v121
	v_cvt_pk_bf16_f32 v115, v122, v123
	v_cvt_pk_bf16_f32 v116, v116, v117
	v_cvt_pk_bf16_f32 v117, v118, v119
	v_cvt_pk_bf16_f32 v118, v154, v155
	v_cvt_pk_bf16_f32 v119, v156, v157
	global_store_dwordx4 v[170:171], v[112:115], off sc1
	global_store_dwordx4 v[170:171], v[116:119], off offset:256 sc1
.LBB0_2030:
	s_or_b64 exec, exec, s[26:27]
	v_or_b32_e32 v112, 16, v146
	v_cmp_gt_i32_e32 vcc, s61, v112
	s_and_saveexec_b64 s[26:27], vcc
	s_cbranch_execz .LBB0_2032
	v_ashrrev_i32_e32 v113, 31, v112
	v_lshlrev_b64 v[154:155], 11, v[112:113]
	v_lshlrev_b64 v[114:115], 12, v[112:113]
	v_lshl_add_u64 v[112:113], s[8:9], 0, v[154:155]
	v_lshl_add_u64 v[116:117], s[10:11], 0, v[114:115]
	v_lshl_add_u64 v[120:121], v[112:113], 0, v[144:145]
	global_load_dwordx4 v[112:115], v[120:121], off
	v_lshl_add_u64 v[124:125], v[116:117], 0, v[144:145]
	global_load_dwordx4 v[116:119], v[124:125], off offset:2048
	s_nop 0
	global_load_dwordx4 v[120:123], v[120:121], off offset:256
	s_nop 0
	global_load_dwordx4 v[124:127], v[124:125], off offset:2304
	v_lshl_add_u64 v[154:155], s[12:13], 0, v[154:155]
	v_lshl_add_u64 v[154:155], v[154:155], 0, v[144:145]
	s_waitcnt vmcnt(0)
	v_lshlrev_b32_e32 v158, 16, v116
	v_lshlrev_b32_e32 v156, 16, v112
	v_and_b32_e32 v157, 0xffff0000, v112
	v_and_b32_e32 v159, 0xffff0000, v116
	v_lshlrev_b32_e32 v112, 16, v113
	v_and_b32_e32 v113, 0xffff0000, v113
	v_lshlrev_b32_e32 v116, 16, v117
	v_and_b32_e32 v117, 0xffff0000, v117
	v_lshlrev_b32_e32 v160, 16, v114
	v_and_b32_e32 v161, 0xffff0000, v114
	v_lshlrev_b32_e32 v162, 16, v118
	v_and_b32_e32 v163, 0xffff0000, v118
	v_lshlrev_b32_e32 v114, 16, v115
	v_and_b32_e32 v115, 0xffff0000, v115
	v_lshlrev_b32_e32 v118, 16, v119
	v_and_b32_e32 v119, 0xffff0000, v119
	v_lshlrev_b32_e32 v164, 16, v120
	v_and_b32_e32 v165, 0xffff0000, v120
	v_lshlrev_b32_e32 v166, 16, v124
	v_and_b32_e32 v167, 0xffff0000, v124
	v_lshlrev_b32_e32 v120, 16, v121
	v_and_b32_e32 v121, 0xffff0000, v121
	v_lshlrev_b32_e32 v124, 16, v125
	v_and_b32_e32 v125, 0xffff0000, v125
	v_lshlrev_b32_e32 v168, 16, v122
	v_and_b32_e32 v169, 0xffff0000, v122
	v_lshlrev_b32_e32 v170, 16, v126
	v_and_b32_e32 v171, 0xffff0000, v126
	v_lshlrev_b32_e32 v122, 16, v123
	v_and_b32_e32 v123, 0xffff0000, v123
	v_lshlrev_b32_e32 v126, 16, v127
	v_and_b32_e32 v127, 0xffff0000, v127
	v_pk_fma_f32 v[108:109], v[108:109], v[158:159], v[156:157]
	v_pk_fma_f32 v[110:111], v[110:111], v[116:117], v[112:113]
	v_pk_fma_f32 v[104:105], v[104:105], v[162:163], v[160:161]
	v_pk_fma_f32 v[106:107], v[106:107], v[118:119], v[114:115]
	v_pk_fma_f32 v[100:101], v[100:101], v[166:167], v[164:165]
	v_pk_fma_f32 v[102:103], v[102:103], v[124:125], v[120:121]
	v_pk_fma_f32 v[112:113], v[96:97], v[170:171], v[168:169]
	v_pk_fma_f32 v[114:115], v[98:99], v[126:127], v[122:123]
	v_cvt_pk_bf16_f32 v96, v108, v109
	v_cvt_pk_bf16_f32 v97, v110, v111
	v_cvt_pk_bf16_f32 v98, v104, v105
	v_cvt_pk_bf16_f32 v99, v106, v107
	v_cvt_pk_bf16_f32 v100, v100, v101
	v_cvt_pk_bf16_f32 v101, v102, v103
	v_cvt_pk_bf16_f32 v102, v112, v113
	v_cvt_pk_bf16_f32 v103, v114, v115
	global_store_dwordx4 v[154:155], v[96:99], off sc1
	global_store_dwordx4 v[154:155], v[100:103], off offset:256 sc1
; __device__ __forceinline__ unsigned pk2(float lo, float hi) { f32x2 v = {lo, hi}; bf16x2_t b = __builtin_convertvector(v, bf16x2_t); return __builtin_bit_cast(unsigned, b); }
; __device__ __forceinline__ float bflo(unsigned w) { return __uint_as_float(w << 16); }
; __device__ __forceinline__ float bfhi(unsigned w) { return __uint_as_float(w & 0xffff0000u); }
;     __device__ __forceinline__ void operator()(const f32x4 (&acc)[2][2][4][2], const Unit& u, int wr, int wc, int fr, int fq) const {
;         const int col0 = u.pn * 256 + wc * 32 + 8 * fq;
; #pragma unroll
;         for (int ai = 0; ai < 2; ++ai)
; #pragma unroll
;             for (int m = 0; m < 4; ++m) {
;                 const int row = u.pm * 256 + ai * 128 + wr * 64 + m * 16 + fr;
;                 if (row < MR) {
; #pragma unroll
;                     for (int bj = 0; bj < 2; ++bj) {
;                         const u32x4 gv = *(const u32x4*)(GATE + (size_t)row * 2048 + 1024 + col0 + bj * 128);
;                         const u32x4 tv = *(const u32x4*)(T + (size_t)row * DM + col0 + bj * 128);
;                         f32x4 a = (f32x4){bflo(tv.x), bfhi(tv.x), bflo(tv.y), bfhi(tv.y)}, b = (f32x4){bflo(tv.z), bfhi(tv.z), bflo(tv.w), bfhi(tv.w)};
;                         const f32x4 x = acc[ai][bj][m][0], y = acc[ai][bj][m][1];
;                         a[0] += x[0] * bflo(gv.x); a[1] += x[1] * bfhi(gv.x); a[2] += x[2] * bflo(gv.y); a[3] += x[3] * bfhi(gv.y);
;                         b[0] += y[0] * bflo(gv.z); b[1] += y[1] * bfhi(gv.z); b[2] += y[2] * bflo(gv.w); b[3] += y[3] * bfhi(gv.w);
;                         u32x4 w; w.x = pk2(a[0], a[1]); w.y = pk2(a[2], a[3]); w.z = pk2(b[0], b[1]); w.w = pk2(b[2], b[3]);
;                         *(u32x4*)(MG + (size_t)row * DM + col0 + bj * 128) = w;
;                     }
;                 }
;                 asm volatile("" ::: "memory");
;             }
.LBB0_2032:
	s_or_b64 exec, exec, s[26:27]
	v_or_b32_e32 v96, 32, v146
	v_cmp_gt_i32_e32 vcc, s61, v96
	s_and_saveexec_b64 s[26:27], vcc
	s_cbranch_execz .LBB0_2034
	v_ashrrev_i32_e32 v97, 31, v96
	v_lshlrev_b64 v[112:113], 11, v[96:97]
	v_lshlrev_b64 v[98:99], 12, v[96:97]
	v_lshl_add_u64 v[96:97], s[8:9], 0, v[112:113]
	v_lshl_add_u64 v[100:101], s[10:11], 0, v[98:99]
	v_lshl_add_u64 v[104:105], v[96:97], 0, v[144:145]
	global_load_dwordx4 v[96:99], v[104:105], off
	v_lshl_add_u64 v[108:109], v[100:101], 0, v[144:145]
	global_load_dwordx4 v[100:103], v[108:109], off offset:2048
	s_nop 0
	global_load_dwordx4 v[104:107], v[104:105], off offset:256
	s_nop 0
	global_load_dwordx4 v[108:111], v[108:109], off offset:2304
	v_lshl_add_u64 v[112:113], s[12:13], 0, v[112:113]
	v_lshl_add_u64 v[112:113], v[112:113], 0, v[144:145]
	s_waitcnt vmcnt(0)
	v_lshlrev_b32_e32 v116, 16, v100
	v_lshlrev_b32_e32 v114, 16, v96
	v_and_b32_e32 v115, 0xffff0000, v96
	v_and_b32_e32 v117, 0xffff0000, v100
	v_lshlrev_b32_e32 v96, 16, v97
	v_and_b32_e32 v97, 0xffff0000, v97
	v_lshlrev_b32_e32 v100, 16, v101
	v_and_b32_e32 v101, 0xffff0000, v101
	v_lshlrev_b32_e32 v118, 16, v98
	v_and_b32_e32 v119, 0xffff0000, v98
	v_lshlrev_b32_e32 v120, 16, v102
	v_and_b32_e32 v121, 0xffff0000, v102
	v_lshlrev_b32_e32 v98, 16, v99
	v_and_b32_e32 v99, 0xffff0000, v99
	v_lshlrev_b32_e32 v102, 16, v103
	v_and_b32_e32 v103, 0xffff0000, v103
	v_lshlrev_b32_e32 v122, 16, v104
	v_and_b32_e32 v123, 0xffff0000, v104
	v_lshlrev_b32_e32 v124, 16, v108
	v_and_b32_e32 v125, 0xffff0000, v108
	v_lshlrev_b32_e32 v104, 16, v105
	v_and_b32_e32 v105, 0xffff0000, v105
	v_lshlrev_b32_e32 v108, 16, v109
	v_and_b32_e32 v109, 0xffff0000, v109
	v_lshlrev_b32_e32 v126, 16, v106
	v_and_b32_e32 v127, 0xffff0000, v106
	v_lshlrev_b32_e32 v154, 16, v110
	v_and_b32_e32 v155, 0xffff0000, v110
	v_lshlrev_b32_e32 v106, 16, v107
	v_and_b32_e32 v107, 0xffff0000, v107
	v_lshlrev_b32_e32 v110, 16, v111
	v_and_b32_e32 v111, 0xffff0000, v111
	v_pk_fma_f32 v[92:93], v[92:93], v[116:117], v[114:115]
	v_pk_fma_f32 v[94:95], v[94:95], v[100:101], v[96:97]
	v_pk_fma_f32 v[88:89], v[88:89], v[120:121], v[118:119]
	v_pk_fma_f32 v[90:91], v[90:91], v[102:103], v[98:99]
	v_pk_fma_f32 v[84:85], v[84:85], v[124:125], v[122:123]
	v_pk_fma_f32 v[86:87], v[86:87], v[108:109], v[104:105]
	v_pk_fma_f32 v[96:97], v[80:81], v[154:155], v[126:127]
	v_pk_fma_f32 v[98:99], v[82:83], v[110:111], v[106:107]
	v_cvt_pk_bf16_f32 v80, v92, v93
	v_cvt_pk_bf16_f32 v81, v94, v95
	v_cvt_pk_bf16_f32 v82, v88, v89
	v_cvt_pk_bf16_f32 v83, v90, v91
	v_cvt_pk_bf16_f32 v84, v84, v85
	v_cvt_pk_bf16_f32 v85, v86, v87
	v_cvt_pk_bf16_f32 v86, v96, v97
	v_cvt_pk_bf16_f32 v87, v98, v99
	global_store_dwordx4 v[112:113], v[80:83], off sc1
	global_store_dwordx4 v[112:113], v[84:87], off offset:256 sc1
.LBB0_2034:
	s_or_b64 exec, exec, s[26:27]
	v_or_b32_e32 v80, 48, v146
	v_cmp_gt_i32_e32 vcc, s61, v80
	s_and_saveexec_b64 s[26:27], vcc
	s_cbranch_execz .LBB0_2036
	v_ashrrev_i32_e32 v81, 31, v80
	v_lshlrev_b64 v[96:97], 11, v[80:81]
	v_lshlrev_b64 v[82:83], 12, v[80:81]
	v_lshl_add_u64 v[80:81], s[8:9], 0, v[96:97]
	v_lshl_add_u64 v[84:85], s[10:11], 0, v[82:83]
	v_lshl_add_u64 v[88:89], v[80:81], 0, v[144:145]
	global_load_dwordx4 v[80:83], v[88:89], off
	v_lshl_add_u64 v[92:93], v[84:85], 0, v[144:145]
	global_load_dwordx4 v[84:87], v[92:93], off offset:2048
	s_nop 0
	global_load_dwordx4 v[88:91], v[88:89], off offset:256
	s_nop 0
	global_load_dwordx4 v[92:95], v[92:93], off offset:2304
	v_lshl_add_u64 v[96:97], s[12:13], 0, v[96:97]
	v_lshl_add_u64 v[96:97], v[96:97], 0, v[144:145]
	s_waitcnt vmcnt(0)
	v_lshlrev_b32_e32 v100, 16, v84
	v_lshlrev_b32_e32 v98, 16, v80
	v_and_b32_e32 v99, 0xffff0000, v80
	v_and_b32_e32 v101, 0xffff0000, v84
	v_lshlrev_b32_e32 v80, 16, v81
	v_and_b32_e32 v81, 0xffff0000, v81
	v_lshlrev_b32_e32 v84, 16, v85
	v_and_b32_e32 v85, 0xffff0000, v85
	v_lshlrev_b32_e32 v102, 16, v82
	v_and_b32_e32 v103, 0xffff0000, v82
	v_lshlrev_b32_e32 v104, 16, v86
	v_and_b32_e32 v105, 0xffff0000, v86
	v_lshlrev_b32_e32 v82, 16, v83
	v_and_b32_e32 v83, 0xffff0000, v83
	v_lshlrev_b32_e32 v86, 16, v87
	v_and_b32_e32 v87, 0xffff0000, v87
	v_lshlrev_b32_e32 v106, 16, v88
	v_and_b32_e32 v107, 0xffff0000, v88
	v_lshlrev_b32_e32 v108, 16, v92
	v_and_b32_e32 v109, 0xffff0000, v92
	v_lshlrev_b32_e32 v88, 16, v89
	v_and_b32_e32 v89, 0xffff0000, v89
	v_lshlrev_b32_e32 v92, 16, v93
	v_and_b32_e32 v93, 0xffff0000, v93
	v_lshlrev_b32_e32 v110, 16, v90
	v_and_b32_e32 v111, 0xffff0000, v90
	v_lshlrev_b32_e32 v112, 16, v94
	v_and_b32_e32 v113, 0xffff0000, v94
	v_lshlrev_b32_e32 v90, 16, v91
	v_and_b32_e32 v91, 0xffff0000, v91
	v_lshlrev_b32_e32 v94, 16, v95
	v_and_b32_e32 v95, 0xffff0000, v95
	v_pk_fma_f32 v[76:77], v[76:77], v[100:101], v[98:99]
	v_pk_fma_f32 v[78:79], v[78:79], v[84:85], v[80:81]
	v_pk_fma_f32 v[72:73], v[72:73], v[104:105], v[102:103]
	v_pk_fma_f32 v[74:75], v[74:75], v[86:87], v[82:83]
	v_pk_fma_f32 v[68:69], v[68:69], v[108:109], v[106:107]
	v_pk_fma_f32 v[70:71], v[70:71], v[92:93], v[88:89]
	v_pk_fma_f32 v[80:81], v[64:65], v[112:113], v[110:111]
	v_pk_fma_f32 v[82:83], v[66:67], v[94:95], v[90:91]
	v_cvt_pk_bf16_f32 v64, v76, v77
	v_cvt_pk_bf16_f32 v65, v78, v79
	v_cvt_pk_bf16_f32 v66, v72, v73
	v_cvt_pk_bf16_f32 v67, v74, v75
	v_cvt_pk_bf16_f32 v68, v68, v69
	v_cvt_pk_bf16_f32 v69, v70, v71
	v_cvt_pk_bf16_f32 v70, v80, v81
	v_cvt_pk_bf16_f32 v71, v82, v83
	global_store_dwordx4 v[96:97], v[64:67], off sc1
	global_store_dwordx4 v[96:97], v[68:71], off offset:256 sc1
; __device__ __forceinline__ unsigned pk2(float lo, float hi) { f32x2 v = {lo, hi}; bf16x2_t b = __builtin_convertvector(v, bf16x2_t); return __builtin_bit_cast(unsigned, b); }
; __device__ __forceinline__ float bflo(unsigned w) { return __uint_as_float(w << 16); }
; __device__ __forceinline__ float bfhi(unsigned w) { return __uint_as_float(w & 0xffff0000u); }
;     __device__ __forceinline__ void operator()(const f32x4 (&acc)[2][2][4][2], const Unit& u, int wr, int wc, int fr, int fq) const {
;         const int col0 = u.pn * 256 + wc * 32 + 8 * fq;
; #pragma unroll
;         for (int ai = 0; ai < 2; ++ai)
; #pragma unroll
;             for (int m = 0; m < 4; ++m) {
;                 const int row = u.pm * 256 + ai * 128 + wr * 64 + m * 16 + fr;
;                 if (row < MR) {
; #pragma unroll
;                     for (int bj = 0; bj < 2; ++bj) {
;                         const u32x4 gv = *(const u32x4*)(GATE + (size_t)row * 2048 + 1024 + col0 + bj * 128);
;                         const u32x4 tv = *(const u32x4*)(T + (size_t)row * DM + col0 + bj * 128);
;                         f32x4 a = (f32x4){bflo(tv.x), bfhi(tv.x), bflo(tv.y), bfhi(tv.y)}, b = (f32x4){bflo(tv.z), bfhi(tv.z), bflo(tv.w), bfhi(tv.w)};
;                         const f32x4 x = acc[ai][bj][m][0], y = acc[ai][bj][m][1];
;                         a[0] += x[0] * bflo(gv.x); a[1] += x[1] * bfhi(gv.x); a[2] += x[2] * bflo(gv.y); a[3] += x[3] * bfhi(gv.y);
;                         b[0] += y[0] * bflo(gv.z); b[1] += y[1] * bfhi(gv.z); b[2] += y[2] * bflo(gv.w); b[3] += y[3] * bfhi(gv.w);
;                         u32x4 w; w.x = pk2(a[0], a[1]); w.y = pk2(a[2], a[3]); w.z = pk2(b[0], b[1]); w.w = pk2(b[2], b[3]);
;                         *(u32x4*)(MG + (size_t)row * DM + col0 + bj * 128) = w;
;                     }
;                 }
;                 asm volatile("" ::: "memory");
;             }
.LBB0_2036:
	s_or_b64 exec, exec, s[26:27]
	v_add_u32_e32 v64, 0x80, v146
	v_cmp_gt_i32_e32 vcc, s61, v64
	s_and_saveexec_b64 s[26:27], vcc
	s_cbranch_execz .LBB0_2038
	v_ashrrev_i32_e32 v65, 31, v64
	v_lshlrev_b64 v[80:81], 11, v[64:65]
	v_lshlrev_b64 v[66:67], 12, v[64:65]
	v_lshl_add_u64 v[64:65], s[8:9], 0, v[80:81]
	v_lshl_add_u64 v[68:69], s[10:11], 0, v[66:67]
	v_lshl_add_u64 v[72:73], v[64:65], 0, v[144:145]
	global_load_dwordx4 v[64:67], v[72:73], off
	v_lshl_add_u64 v[76:77], v[68:69], 0, v[144:145]
	global_load_dwordx4 v[68:71], v[76:77], off offset:2048
	s_nop 0
	global_load_dwordx4 v[72:75], v[72:73], off offset:256
	s_nop 0
	global_load_dwordx4 v[76:79], v[76:77], off offset:2304
	v_lshl_add_u64 v[80:81], s[12:13], 0, v[80:81]
	v_lshl_add_u64 v[80:81], v[80:81], 0, v[144:145]
	s_waitcnt vmcnt(0)
	v_lshlrev_b32_e32 v84, 16, v68
	v_lshlrev_b32_e32 v82, 16, v64
	v_and_b32_e32 v83, 0xffff0000, v64
	v_and_b32_e32 v85, 0xffff0000, v68
	v_lshlrev_b32_e32 v64, 16, v65
	v_and_b32_e32 v65, 0xffff0000, v65
	v_lshlrev_b32_e32 v68, 16, v69
	v_and_b32_e32 v69, 0xffff0000, v69
	v_lshlrev_b32_e32 v86, 16, v66
	v_and_b32_e32 v87, 0xffff0000, v66
	v_lshlrev_b32_e32 v88, 16, v70
	v_and_b32_e32 v89, 0xffff0000, v70
	v_lshlrev_b32_e32 v66, 16, v67
	v_and_b32_e32 v67, 0xffff0000, v67
	v_lshlrev_b32_e32 v70, 16, v71
	v_and_b32_e32 v71, 0xffff0000, v71
	v_lshlrev_b32_e32 v90, 16, v72
	v_and_b32_e32 v91, 0xffff0000, v72
	v_lshlrev_b32_e32 v92, 16, v76
	v_and_b32_e32 v93, 0xffff0000, v76
	v_lshlrev_b32_e32 v72, 16, v73
	v_and_b32_e32 v73, 0xffff0000, v73
	v_lshlrev_b32_e32 v76, 16, v77
	v_and_b32_e32 v77, 0xffff0000, v77
	v_lshlrev_b32_e32 v94, 16, v74
	v_and_b32_e32 v95, 0xffff0000, v74
	v_lshlrev_b32_e32 v96, 16, v78
	v_and_b32_e32 v97, 0xffff0000, v78
	v_lshlrev_b32_e32 v74, 16, v75
	v_and_b32_e32 v75, 0xffff0000, v75
	v_lshlrev_b32_e32 v78, 16, v79
	v_and_b32_e32 v79, 0xffff0000, v79
	v_pk_fma_f32 v[60:61], v[60:61], v[84:85], v[82:83]
	v_pk_fma_f32 v[62:63], v[62:63], v[68:69], v[64:65]
	v_pk_fma_f32 v[56:57], v[56:57], v[88:89], v[86:87]
	v_pk_fma_f32 v[58:59], v[58:59], v[70:71], v[66:67]
	v_pk_fma_f32 v[52:53], v[52:53], v[92:93], v[90:91]
	v_pk_fma_f32 v[54:55], v[54:55], v[76:77], v[72:73]
	v_pk_fma_f32 v[64:65], v[48:49], v[96:97], v[94:95]
	v_pk_fma_f32 v[66:67], v[50:51], v[78:79], v[74:75]
	v_cvt_pk_bf16_f32 v48, v60, v61
	v_cvt_pk_bf16_f32 v49, v62, v63
	v_cvt_pk_bf16_f32 v50, v56, v57
	v_cvt_pk_bf16_f32 v51, v58, v59
	v_cvt_pk_bf16_f32 v52, v52, v53
	v_cvt_pk_bf16_f32 v53, v54, v55
	v_cvt_pk_bf16_f32 v54, v64, v65
	v_cvt_pk_bf16_f32 v55, v66, v67
	global_store_dwordx4 v[80:81], v[48:51], off sc1
	global_store_dwordx4 v[80:81], v[52:55], off offset:256 sc1
.LBB0_2038:
	s_or_b64 exec, exec, s[26:27]
	v_add_u32_e32 v48, 0x90, v146
	v_cmp_gt_i32_e32 vcc, s61, v48
	s_and_saveexec_b64 s[26:27], vcc
	s_cbranch_execz .LBB0_2040
	v_ashrrev_i32_e32 v49, 31, v48
	v_lshlrev_b64 v[64:65], 11, v[48:49]
	v_lshlrev_b64 v[50:51], 12, v[48:49]
	v_lshl_add_u64 v[48:49], s[8:9], 0, v[64:65]
	v_lshl_add_u64 v[52:53], s[10:11], 0, v[50:51]
	v_lshl_add_u64 v[56:57], v[48:49], 0, v[144:145]
	global_load_dwordx4 v[48:51], v[56:57], off
	v_lshl_add_u64 v[60:61], v[52:53], 0, v[144:145]
	global_load_dwordx4 v[52:55], v[60:61], off offset:2048
	s_nop 0
	global_load_dwordx4 v[56:59], v[56:57], off offset:256
	s_nop 0
	global_load_dwordx4 v[60:63], v[60:61], off offset:2304
	v_lshl_add_u64 v[64:65], s[12:13], 0, v[64:65]
	v_lshl_add_u64 v[64:65], v[64:65], 0, v[144:145]
	s_waitcnt vmcnt(0)
	v_lshlrev_b32_e32 v68, 16, v52
	v_lshlrev_b32_e32 v66, 16, v48
	v_and_b32_e32 v67, 0xffff0000, v48
	v_and_b32_e32 v69, 0xffff0000, v52
	v_lshlrev_b32_e32 v48, 16, v49
	v_and_b32_e32 v49, 0xffff0000, v49
	v_lshlrev_b32_e32 v52, 16, v53
	v_and_b32_e32 v53, 0xffff0000, v53
	v_lshlrev_b32_e32 v70, 16, v50
	v_and_b32_e32 v71, 0xffff0000, v50
	v_lshlrev_b32_e32 v72, 16, v54
	v_and_b32_e32 v73, 0xffff0000, v54
	v_lshlrev_b32_e32 v50, 16, v51
	v_and_b32_e32 v51, 0xffff0000, v51
	v_lshlrev_b32_e32 v54, 16, v55
	v_and_b32_e32 v55, 0xffff0000, v55
	v_lshlrev_b32_e32 v74, 16, v56
	v_and_b32_e32 v75, 0xffff0000, v56
	v_lshlrev_b32_e32 v76, 16, v60
	v_and_b32_e32 v77, 0xffff0000, v60
	v_lshlrev_b32_e32 v56, 16, v57
	v_and_b32_e32 v57, 0xffff0000, v57
	v_lshlrev_b32_e32 v60, 16, v61
	v_and_b32_e32 v61, 0xffff0000, v61
	v_lshlrev_b32_e32 v78, 16, v58
	v_and_b32_e32 v79, 0xffff0000, v58
	v_lshlrev_b32_e32 v80, 16, v62
	v_and_b32_e32 v81, 0xffff0000, v62
	v_lshlrev_b32_e32 v58, 16, v59
	v_and_b32_e32 v59, 0xffff0000, v59
	v_lshlrev_b32_e32 v62, 16, v63
	v_and_b32_e32 v63, 0xffff0000, v63
	v_pk_fma_f32 v[44:45], v[44:45], v[68:69], v[66:67]
	v_pk_fma_f32 v[46:47], v[46:47], v[52:53], v[48:49]
	v_pk_fma_f32 v[40:41], v[40:41], v[72:73], v[70:71]
	v_pk_fma_f32 v[42:43], v[42:43], v[54:55], v[50:51]
	v_pk_fma_f32 v[36:37], v[36:37], v[76:77], v[74:75]
	v_pk_fma_f32 v[38:39], v[38:39], v[60:61], v[56:57]
	v_pk_fma_f32 v[48:49], v[32:33], v[80:81], v[78:79]
	v_pk_fma_f32 v[50:51], v[34:35], v[62:63], v[58:59]
	v_cvt_pk_bf16_f32 v32, v44, v45
	v_cvt_pk_bf16_f32 v33, v46, v47
	v_cvt_pk_bf16_f32 v34, v40, v41
	v_cvt_pk_bf16_f32 v35, v42, v43
	v_cvt_pk_bf16_f32 v36, v36, v37
	v_cvt_pk_bf16_f32 v37, v38, v39
	v_cvt_pk_bf16_f32 v38, v48, v49
	v_cvt_pk_bf16_f32 v39, v50, v51
	global_store_dwordx4 v[64:65], v[32:35], off sc1
	global_store_dwordx4 v[64:65], v[36:39], off offset:256 sc1
; __device__ __forceinline__ unsigned pk2(float lo, float hi) { f32x2 v = {lo, hi}; bf16x2_t b = __builtin_convertvector(v, bf16x2_t); return __builtin_bit_cast(unsigned, b); }
; __device__ __forceinline__ float bflo(unsigned w) { return __uint_as_float(w << 16); }
; __device__ __forceinline__ float bfhi(unsigned w) { return __uint_as_float(w & 0xffff0000u); }
;     __device__ __forceinline__ void operator()(const f32x4 (&acc)[2][2][4][2], const Unit& u, int wr, int wc, int fr, int fq) const {
;         const int col0 = u.pn * 256 + wc * 32 + 8 * fq;
; #pragma unroll
;         for (int ai = 0; ai < 2; ++ai)
; #pragma unroll
;             for (int m = 0; m < 4; ++m) {
;                 const int row = u.pm * 256 + ai * 128 + wr * 64 + m * 16 + fr;
;                 if (row < MR) {
; #pragma unroll
;                     for (int bj = 0; bj < 2; ++bj) {
;                         const u32x4 gv = *(const u32x4*)(GATE + (size_t)row * 2048 + 1024 + col0 + bj * 128);
;                         const u32x4 tv = *(const u32x4*)(T + (size_t)row * DM + col0 + bj * 128);
;                         f32x4 a = (f32x4){bflo(tv.x), bfhi(tv.x), bflo(tv.y), bfhi(tv.y)}, b = (f32x4){bflo(tv.z), bfhi(tv.z), bflo(tv.w), bfhi(tv.w)};
;                         const f32x4 x = acc[ai][bj][m][0], y = acc[ai][bj][m][1];
;                         a[0] += x[0] * bflo(gv.x); a[1] += x[1] * bfhi(gv.x); a[2] += x[2] * bflo(gv.y); a[3] += x[3] * bfhi(gv.y);
;                         b[0] += y[0] * bflo(gv.z); b[1] += y[1] * bfhi(gv.z); b[2] += y[2] * bflo(gv.w); b[3] += y[3] * bfhi(gv.w);
;                         u32x4 w; w.x = pk2(a[0], a[1]); w.y = pk2(a[2], a[3]); w.z = pk2(b[0], b[1]); w.w = pk2(b[2], b[3]);
;                         *(u32x4*)(MG + (size_t)row * DM + col0 + bj * 128) = w;
;                     }
;                 }
;                 asm volatile("" ::: "memory");
;             }
;     }
.LBB0_2040:
	s_or_b64 exec, exec, s[26:27]
	v_add_u32_e32 v32, 0xa0, v146
	v_cmp_gt_i32_e32 vcc, s61, v32
	s_and_saveexec_b64 s[26:27], vcc
	s_cbranch_execz .LBB0_2042
	v_ashrrev_i32_e32 v33, 31, v32
	v_lshlrev_b64 v[48:49], 11, v[32:33]
	v_lshlrev_b64 v[34:35], 12, v[32:33]
	v_lshl_add_u64 v[32:33], s[8:9], 0, v[48:49]
	v_lshl_add_u64 v[36:37], s[10:11], 0, v[34:35]
	v_lshl_add_u64 v[40:41], v[32:33], 0, v[144:145]
	global_load_dwordx4 v[32:35], v[40:41], off
	v_lshl_add_u64 v[44:45], v[36:37], 0, v[144:145]
	global_load_dwordx4 v[36:39], v[44:45], off offset:2048
	s_nop 0
	global_load_dwordx4 v[40:43], v[40:41], off offset:256
	s_nop 0
	global_load_dwordx4 v[44:47], v[44:45], off offset:2304
	v_lshl_add_u64 v[48:49], s[12:13], 0, v[48:49]
	v_lshl_add_u64 v[48:49], v[48:49], 0, v[144:145]
	s_waitcnt vmcnt(0)
	v_lshlrev_b32_e32 v52, 16, v36
	v_lshlrev_b32_e32 v50, 16, v32
	v_and_b32_e32 v51, 0xffff0000, v32
	v_and_b32_e32 v53, 0xffff0000, v36
	v_lshlrev_b32_e32 v32, 16, v33
	v_and_b32_e32 v33, 0xffff0000, v33
	v_lshlrev_b32_e32 v36, 16, v37
	v_and_b32_e32 v37, 0xffff0000, v37
	v_lshlrev_b32_e32 v54, 16, v34
	v_and_b32_e32 v55, 0xffff0000, v34
	v_lshlrev_b32_e32 v56, 16, v38
	v_and_b32_e32 v57, 0xffff0000, v38
	v_lshlrev_b32_e32 v34, 16, v35
	v_and_b32_e32 v35, 0xffff0000, v35
	v_lshlrev_b32_e32 v38, 16, v39
	v_and_b32_e32 v39, 0xffff0000, v39
	v_lshlrev_b32_e32 v58, 16, v40
	v_and_b32_e32 v59, 0xffff0000, v40
	v_lshlrev_b32_e32 v60, 16, v44
	v_and_b32_e32 v61, 0xffff0000, v44
	v_lshlrev_b32_e32 v40, 16, v41
	v_and_b32_e32 v41, 0xffff0000, v41
	v_lshlrev_b32_e32 v44, 16, v45
	v_and_b32_e32 v45, 0xffff0000, v45
	v_lshlrev_b32_e32 v62, 16, v42
	v_and_b32_e32 v63, 0xffff0000, v42
	v_lshlrev_b32_e32 v64, 16, v46
	v_and_b32_e32 v65, 0xffff0000, v46
	v_lshlrev_b32_e32 v42, 16, v43
	v_and_b32_e32 v43, 0xffff0000, v43
	v_lshlrev_b32_e32 v46, 16, v47
	v_and_b32_e32 v47, 0xffff0000, v47
	v_pk_fma_f32 v[28:29], v[28:29], v[52:53], v[50:51]
	v_pk_fma_f32 v[30:31], v[30:31], v[36:37], v[32:33]
	v_pk_fma_f32 v[24:25], v[24:25], v[56:57], v[54:55]
	v_pk_fma_f32 v[26:27], v[26:27], v[38:39], v[34:35]
	v_pk_fma_f32 v[20:21], v[20:21], v[60:61], v[58:59]
	v_pk_fma_f32 v[22:23], v[22:23], v[44:45], v[40:41]
	v_pk_fma_f32 v[32:33], v[16:17], v[64:65], v[62:63]
	v_pk_fma_f32 v[34:35], v[18:19], v[46:47], v[42:43]
	v_cvt_pk_bf16_f32 v16, v28, v29
	v_cvt_pk_bf16_f32 v17, v30, v31
	v_cvt_pk_bf16_f32 v18, v24, v25
	v_cvt_pk_bf16_f32 v19, v26, v27
	v_cvt_pk_bf16_f32 v20, v20, v21
	v_cvt_pk_bf16_f32 v21, v22, v23
	v_cvt_pk_bf16_f32 v22, v32, v33
	v_cvt_pk_bf16_f32 v23, v34, v35
	global_store_dwordx4 v[48:49], v[16:19], off sc1
	global_store_dwordx4 v[48:49], v[20:23], off offset:256 sc1
.LBB0_2042:
	s_or_b64 exec, exec, s[26:27]
	v_add_u32_e32 v16, 0xb0, v146
	v_cmp_gt_i32_e32 vcc, s61, v16
	s_and_saveexec_b64 s[26:27], vcc
	s_cbranch_execz .LBB0_2044
	v_ashrrev_i32_e32 v17, 31, v16
	v_lshlrev_b64 v[32:33], 11, v[16:17]
	v_lshlrev_b64 v[18:19], 12, v[16:17]
	v_lshl_add_u64 v[16:17], s[8:9], 0, v[32:33]
	v_lshl_add_u64 v[20:21], s[10:11], 0, v[18:19]
	v_lshl_add_u64 v[24:25], v[16:17], 0, v[144:145]
	global_load_dwordx4 v[16:19], v[24:25], off
	v_lshl_add_u64 v[28:29], v[20:21], 0, v[144:145]
	global_load_dwordx4 v[20:23], v[28:29], off offset:2048
	s_nop 0
	global_load_dwordx4 v[24:27], v[24:25], off offset:256
	s_nop 0
	global_load_dwordx4 v[28:31], v[28:29], off offset:2304
	v_lshl_add_u64 v[32:33], s[12:13], 0, v[32:33]
	v_lshl_add_u64 v[32:33], v[32:33], 0, v[144:145]
	s_waitcnt vmcnt(0)
	v_lshlrev_b32_e32 v36, 16, v20
	v_lshlrev_b32_e32 v34, 16, v16
	v_and_b32_e32 v35, 0xffff0000, v16
	v_and_b32_e32 v37, 0xffff0000, v20
	v_lshlrev_b32_e32 v16, 16, v17
	v_and_b32_e32 v17, 0xffff0000, v17
	v_lshlrev_b32_e32 v20, 16, v21
	v_and_b32_e32 v21, 0xffff0000, v21
	v_lshlrev_b32_e32 v38, 16, v18
	v_and_b32_e32 v39, 0xffff0000, v18
	v_lshlrev_b32_e32 v40, 16, v22
	v_and_b32_e32 v41, 0xffff0000, v22
	v_lshlrev_b32_e32 v18, 16, v19
	v_and_b32_e32 v19, 0xffff0000, v19
	v_lshlrev_b32_e32 v22, 16, v23
	v_and_b32_e32 v23, 0xffff0000, v23
	v_lshlrev_b32_e32 v42, 16, v24
	v_and_b32_e32 v43, 0xffff0000, v24
	v_lshlrev_b32_e32 v44, 16, v28
	v_and_b32_e32 v45, 0xffff0000, v28
	v_lshlrev_b32_e32 v24, 16, v25
	v_and_b32_e32 v25, 0xffff0000, v25
	v_lshlrev_b32_e32 v28, 16, v29
	v_and_b32_e32 v29, 0xffff0000, v29
	v_lshlrev_b32_e32 v46, 16, v26
	v_and_b32_e32 v47, 0xffff0000, v26
	v_lshlrev_b32_e32 v48, 16, v30
	v_and_b32_e32 v49, 0xffff0000, v30
	v_lshlrev_b32_e32 v26, 16, v27
	v_and_b32_e32 v27, 0xffff0000, v27
	v_lshlrev_b32_e32 v30, 16, v31
	v_and_b32_e32 v31, 0xffff0000, v31
	v_pk_fma_f32 v[12:13], v[12:13], v[36:37], v[34:35]
	v_pk_fma_f32 v[14:15], v[14:15], v[20:21], v[16:17]
	v_pk_fma_f32 v[8:9], v[8:9], v[40:41], v[38:39]
	v_pk_fma_f32 v[10:11], v[10:11], v[22:23], v[18:19]
	v_pk_fma_f32 v[4:5], v[4:5], v[44:45], v[42:43]
	v_pk_fma_f32 v[6:7], v[6:7], v[28:29], v[24:25]
	v_pk_fma_f32 v[16:17], v[0:1], v[48:49], v[46:47]
	v_pk_fma_f32 v[18:19], v[2:3], v[30:31], v[26:27]
	v_cvt_pk_bf16_f32 v0, v12, v13
	v_cvt_pk_bf16_f32 v1, v14, v15
	v_cvt_pk_bf16_f32 v2, v8, v9
	v_cvt_pk_bf16_f32 v3, v10, v11
	v_cvt_pk_bf16_f32 v4, v4, v5
	v_cvt_pk_bf16_f32 v5, v6, v7
	v_cvt_pk_bf16_f32 v6, v16, v17
	v_cvt_pk_bf16_f32 v7, v18, v19
	global_store_dwordx4 v[32:33], v[0:3], off sc1
	global_store_dwordx4 v[32:33], v[4:7], off offset:256 sc1

; #define PG8_WAIT_V(n) asm volatile("s_waitcnt vmcnt(" #n ")" ::: "memory")
; #define PG8_BAR __builtin_amdgcn_s_barrier()
;     __host__ __device__ bool next(int i, Unit& u) const {
;         const long L = (long)i * G + c; if (L >= nwg) return false;
;         int wgid = (int)L; { const int q = nwg / NXCD, r = nwg % NXCD, xcd = wgid % NXCD, off = wgid / NXCD; wgid = (xcd < r ? xcd * (q + 1) : r * (q + 1) + (xcd - r) * q) + off; }
;         const int nig = WGM * nN, gid = wgid / nig, fm = gid * WGM, gsz = (nM - fm) < WGM ? (nM - fm) : WGM;
;         u.pm = fm + ((wgid % nig) % gsz); u.pn = (wgid % nig) / gsz; return true;
; template <class Epi, class Sched, bool ALIGN_EPI = false, bool SP2 = false>
; __device__ __forceinline__ void gemm_phase(PG8_LAS unsigned char* lds, const Gemm g, const Sched& S, const Epi& E) {
;     ...
;     PG8_WAIT_V(0);
;     if constexpr (!ALIGN_EPI) { if (wr == 0) PG8_BAR; }
;     PG8_BAR;
.LBB0_2047:
	s_waitcnt vmcnt(0)
	s_barrier
	v_cmp_eq_u32_e32 vcc, 0, v180
	s_and_saveexec_b64 s[46:47], vcc
	s_cbranch_execz .Lp89_sig
	s_waitcnt vmcnt(0)
	s_add_u32 s40, s30, 0x3180a00
	s_addc_u32 s41, s31, 0
	s_and_b32 s42, s28, 7
	s_lshr_b32 s43, s28, 3
	s_mul_i32 s44, s42, 33
	s_lshl_b32 s45, s42, 5
	s_add_i32 s45, s45, 4
	s_cmp_lt_u32 s42, 4
	s_cselect_b32 s44, s44, s45
	s_add_i32 s44, s44, s43
	s_lshr_b32 s45, s44, 5
	s_and_b32 s43, s44, 7
	s_lshl_b32 s42, s45, 3
	s_add_i32 s42, s42, s43
	s_cmp_lt_u32 s45, 8
	s_cselect_b32 s42, s42, 64
	s_lshl_b32 s42, s42, 2
	v_mov_b32_e32 v230, s42
	v_mov_b32_e32 v231, 1
	v_mov_b32_e32 v233, 0x140
	global_atomic_add v230, v231, s[40:41]
	global_atomic_add v233, v231, s[40:41]
	s_cmp_lt_u32 s28, 4
	s_cbranch_scc0 .Lp89_sig
	s_mul_i32 s42, s28, 9
	s_add_i32 s42, s42, 8
	s_lshl_b32 s42, s42, 2
	v_mov_b32_e32 v232, s42
	global_atomic_add v232, v231, s[40:41]
	global_atomic_add v233, v231, s[40:41]

;     __device__ __forceinline__ unsigned char* ws() const { return (unsigned char*)ptr(37); }
; #define ws (p.ws())
; #define SEAM(k) do { if (IN(k) && IN((k) + 1)) xcd_barrier(bar); } while (0)
;     __host__ __device__ bool next(int i, Unit& u) const {
;         const long L = (long)i * G + c; if (L >= nwg) return false;
;         int wgid = (int)L; { const int q = nwg / NXCD, r = nwg % NXCD, xcd = wgid % NXCD, off = wgid / NXCD; wgid = (xcd < r ? xcd * (q + 1) : r * (q + 1) + (xcd - r) * q) + off; }
;         const int nig = WGM * nN, gid = wgid / nig, fm = gid * WGM, gsz = (nM - fm) < WGM ? (nM - fm) : WGM;
;         u.pm = fm + ((wgid % nig) % gsz); u.pn = (wgid % nig) / gsz; return true;
; __global__ void __launch_bounds__(512) fwd_kernel(Params prm) {
;     ...
;     if (IN(8)) { EpiGate2 E{(const bf16_t*)(ws + WS_KB), (const bf16_t*)(ws + WS_GATE), (bf16_t*)(ws + WS_MG)}; run_gemm(lds, (const bf16_t*)(ws + WS_ORW), (const bf16_t*)(ws + WS_WRT), DM, 512, E); } SEAM(8);
;     if (IN(9)) { EpiF32 E{(float*)(ws + WS_T)}; run_gemm(lds, (const bf16_t*)(ws + WS_MG), (const bf16_t*)(ws + WS_WOT), DM, DM, E, MPR); run_gemm_sample(lds, (const bf16_t*)(ws + WS_MG), (const bf16_t*)(ws + WS_WOT), DM, (float*)(ws + WS_PART)); } SEAM(9);
.LBB0_2102:
	s_cmp_lt_i32 s36, 10
	s_cselect_b64 s[4:5], -1, 0
	s_and_b64 s[4:5], s[4:5], s[2:3]
	s_andn2_b64 vcc, exec, s[4:5]
	s_cbranch_vccnz .LBB0_2151
	v_cmp_eq_u32_e32 vcc, 0, v180
	s_and_saveexec_b64 s[46:47], vcc
	s_cbranch_execz .Lp89_w
	s_add_u32 s40, s30, 0x3180a00
	s_addc_u32 s41, s31, 0
	s_and_b32 s42, s28, 7
	s_lshl_b32 s42, s42, 3
	s_bfe_u32 s43, s28, 0x30003
	s_add_i32 s44, s42, s43
	s_lshl_b32 s42, s44, 2
	s_mov_b32 s45, 0
.Lp89_next:
	s_lshl_b32 s43, s44, 2
	v_mov_b32_e32 v230, s43
.Lp89_a_spin:
	global_load_dword v231, v230, s[40:41] sc1
	s_waitcnt vmcnt(0)
	v_cmp_gt_u32_e32 vcc, 4, v231
	s_cbranch_vccz .Lp89_a_ok
	s_sleep 2
	s_branch .Lp89_a_spin
.Lp89_a_ok:
	s_cmp_gt_u32 s42, 64
	s_cbranch_scc1 .Lp89_acq
	s_cmp_eq_u32 s45, 4
	s_cbranch_scc1 .Lp89_acq
	s_add_i32 s44, s42, s45
	s_min_u32 s44, s44, 64
	s_add_i32 s45, s45, 1
	s_branch .Lp89_next

; #define LAS __attribute__((address_space(3)))
;     __device__ __forceinline__ bool next(int i, pg8::Unit& u) const { if (i > 0 || !on) return false; u.pm = 0; u.pn = pn; return true; }
;     __host__ __device__ bool next(int i, Unit& u) const {
;         const long L = (long)i * G + c; if (L >= nwg) return false;
;         int wgid = (int)L; { const int q = nwg / NXCD, r = nwg % NXCD, xcd = wgid % NXCD, off = wgid / NXCD; wgid = (xcd < r ? xcd * (q + 1) : r * (q + 1) + (xcd - r) * q) + off; }
;         const int nig = WGM * nN, gid = wgid / nig, fm = gid * WGM, gsz = (nM - fm) < WGM ? (nM - fm) : WGM;
;         u.pm = fm + ((wgid % nig) % gsz); u.pn = (wgid % nig) / gsz; return true;
; template <class Epi> __device__ __forceinline__ void run_gemm(LAS unsigned char* lds, const bf16_t* A, const bf16_t* Bt, int N, int K, const Epi& E, int M = MP) {
;     pg8::Gemm g{A, Bt, M, N, K, K}; pg8::StaticOrder S; S.init(M, N, (int)gridDim.x, (int)blockIdx.x);
;     pg8::gemm_phase<Epi, pg8::StaticOrder, true, true>(lds, g, S, E);
.Lp89_w:
	s_or_b64 exec, exec, s[46:47]
	s_barrier
	s_add_i32 s2, 0, 0x23528
	s_waitcnt vmcnt(0)
	v_mov_b32_e32 v0, s2
	ds_read_b64 v[0:1], v0
	s_cmpk_lt_i32 s28, 0x100
	s_cselect_b64 s[2:3], -1, 0
	s_cmpk_gt_i32 s28, 0xff
	v_readfirstlane_b32 s12, v180
	s_waitcnt lgkmcnt(0)
	v_readfirstlane_b32 s8, v0
	v_readfirstlane_b32 s9, v1
	s_cbranch_scc1 .LBB0_2109
	s_ashr_i32 s6, s28, 31
	s_lshr_b32 s6, s6, 29
	s_add_i32 s10, s28, s6
	s_and_b32 s6, s10, -8
	s_sub_i32 s11, s28, s6
	s_cmp_gt_i32 s11, -1
	s_cbranch_scc0 .LBB0_2106
	s_lshl_b32 s13, s11, 5
	s_cbranch_execz .LBB0_2107
	s_branch .LBB0_2108

; #define LAS __attribute__((address_space(3)))
; __device__ __forceinline__ void run_gemm_sample(LAS unsigned char* lds, const bf16_t* A, const bf16_t* Bt, int K, float* PART) {
;     const int c = (int)blockIdx.x, ns = K / KSL, ks = c >> 2;
;     OneUnit S{c & 3, c < 4 * ns};
;     pg8::Gemm g{A + (size_t)MPR * K + (size_t)ks * KSL, Bt + (size_t)ks * KSL, 256, DM, KSL, K};
;     EpiPart E{PART + (size_t)ks * 128 * DM};
;     pg8::gemm_phase<EpiPart, OneUnit, false, true>(lds, g, S, E);
.LBB0_2145:
	s_waitcnt lgkmcnt(0)
	v_readfirstlane_b32 s14, v0
	v_readfirstlane_b32 s16, v1
	s_sub_u32 s9, s28, 32
	s_cmp_gt_u32 s9, 15
	v_readfirstlane_b32 s10, v180
	s_cbranch_scc1 .LBB0_2151
	v_cmp_eq_u32_e32 vcc, 0, v180
	s_and_saveexec_b64 s[46:47], vcc
	s_cbranch_execz .Lp89_u
	s_add_u32 s40, s30, 0x3180a00
	s_addc_u32 s41, s31, 0
	v_mov_b32_e32 v230, 0x140
.Lp89_b_spin:
	global_load_dword v231, v230, s[40:41] sc1
	s_waitcnt vmcnt(0)
	v_cmp_gt_u32_e32 vcc, 260, v231
	s_cbranch_vccz .Lp89_b_ok
	s_sleep 2
	s_branch .Lp89_b_spin

; #define PG8_STAGE(bufoff, gbase, voff) do { _Pragma("unroll") for (int _i = 0; _i < 2; ++_i) \
;         __builtin_amdgcn_global_load_lds((const unsigned*)((const char*)(gbase) + (voff)[_i]), (PG8_LAS unsigned*)(lds + (bufoff) + ldsw + _i * 8192), 16, 0, 0); } while (0)
; #define PG8_WAIT_V(n) asm volatile("s_waitcnt vmcnt(" #n ")" ::: "memory")
; #define PG8_BAR __builtin_amdgcn_s_barrier()
; #define LAS __attribute__((address_space(3)))
; template <class Epi, class Sched, bool ALIGN_EPI = false, bool SP2 = false>
; __device__ __forceinline__ void gemm_phase(PG8_LAS unsigned char* lds, const Gemm g, const Sched& S, const Epi& E) {
;     ...
;     if constexpr (SP2) {
;         PG8_STAGE(PG8_SB(0, 0), cB, voffB); PG8_STAGE(PG8_SB(0, 1), cB + hstep, voffB); PG8_STAGE(PG8_SA(0, 0), cA, voffA); PG8_STAGE(PG8_SA(0, 1), cA + hstep, voffA);
;         if (wr == 1) PG8_BAR;
;         PG8_WAIT_V(2); PG8_BAR;
;         PG8_STAGE(PG8_SB(1, 0), cB + kstep, voffB); PG8_STAGE(PG8_SA(1, 0), cA + kstep, voffA); PG8_STAGE(PG8_SB(1, 1), cB + hstep + kstep, voffB);
;         PG8_WAIT_V(6); PG8_BAR;
; __device__ __forceinline__ void run_gemm_sample(LAS unsigned char* lds, const bf16_t* A, const bf16_t* Bt, int K, float* PART) {
;     const int c = (int)blockIdx.x, ns = K / KSL, ks = c >> 2;
;     OneUnit S{c & 3, c < 4 * ns};
;     pg8::Gemm g{A + (size_t)MPR * K + (size_t)ks * KSL, Bt + (size_t)ks * KSL, 256, DM, KSL, K};
;     EpiPart E{PART + (size_t)ks * 128 * DM};
;     pg8::gemm_phase<EpiPart, OneUnit, false, true>(lds, g, S, E);
.Lp89_u:
	s_or_b64 exec, exec, s[46:47]
	s_barrier
	s_ashr_i32 s8, s9, 2
	s_ashr_i32 s9, s8, 31
	s_and_b32 s11, s28, 3
	s_lshl_b64 s[2:3], s[8:9], 9
	s_add_u32 s13, s14, s2
	s_addc_u32 s15, s16, s3
	s_add_u32 s2, s13, 0x5200000
	s_addc_u32 s3, s15, 0
	s_lshr_b32 s17, s10, 6
	s_lshr_b32 s22, s10, 8
	s_lshl_b32 s21, s17, 10
	s_lshl_b32 s6, s11, 19
	s_add_u32 s18, s13, s6
	s_addc_u32 s19, s15, 0
	s_add_u32 s6, s18, 0x1d00000
	s_addc_u32 s7, s19, 0
	s_add_i32 s12, s21, 0
	s_add_i32 m0, s12, 0x10000
	v_mov_b32_e32 v129, 0
	global_load_lds_dwordx4 v128, s[6:7]
	s_add_i32 m0, s12, 0x12000
	s_add_u32 s18, s18, 0x1d40000
	global_load_lds_dwordx4 v130, s[6:7]
	s_addc_u32 s19, s19, 0
	s_add_i32 m0, s12, 0x14000
	s_add_i32 s20, s12, 0x2000
	global_load_lds_dwordx4 v128, s[18:19]
	s_add_i32 m0, s12, 0x16000
	s_add_u32 s24, s13, 0x5240000
	global_load_lds_dwordx4 v130, s[18:19]
	s_mov_b32 m0, s12
	s_addc_u32 s25, s15, 0
	global_load_lds_dwordx4 v128, s[2:3]
	s_mov_b32 m0, s20
	s_add_i32 s13, s12, 0x4000
	global_load_lds_dwordx4 v130, s[2:3]
	s_mov_b32 m0, s13
	s_add_i32 s15, s12, 0x6000
	global_load_lds_dwordx4 v128, s[24:25]
	s_mov_b32 m0, s15
	v_mov_b32_e32 v131, v129
	global_load_lds_dwordx4 v130, s[24:25]
	v_lshl_add_u64 v[32:33], s[6:7], 0, v[128:129]
	v_lshl_add_u64 v[34:35], s[6:7], 0, v[130:131]
	v_lshl_add_u64 v[30:31], s[18:19], 0, v[128:129]
	v_lshl_add_u64 v[26:27], s[18:19], 0, v[130:131]
	v_lshl_add_u64 v[24:25], s[2:3], 0, v[128:129]
	v_lshl_add_u64 v[22:23], s[2:3], 0, v[130:131]
	v_lshl_add_u64 v[12:13], s[24:25], 0, v[128:129]
	s_cmp_lg_u32 s22, 1
	v_lshl_add_u64 v[14:15], s[24:25], 0, v[130:131]
	s_cbranch_scc1 .LBB0_2148
	s_barrier
